# split-phase P5->P6 grid barrier: arrive after P5a, run P5b (PLE projection GEMM) inside the barrier window, then wait
# baseline (speedup 1.0000x reference)
.LBB0_979:
	s_or_b64 exec, exec, s[6:7]
	s_ashr_i32 s17, s16, 31
	s_lshl_b64 s[6:7], s[16:17], 12
	s_add_u32 s8, s52, s6
	s_addc_u32 s9, s53, s7
	s_ashr_i32 s15, s14, 31
	s_lshl_b64 s[6:7], s[14:15], 1
	s_add_u32 s6, s8, s6
	v_ashrrev_i32_e32 v0, 5, v189
	v_readlane_b32 s8, v250, 0
	v_bfe_u32 v17, v189, 2, 1
	v_and_b32_e32 v18, 48, v190
	s_waitcnt lgkmcnt(1)
	v_add_u32_e32 v2, s8, v0
	v_lshrrev_b32_e32 v0, 2, v189
	v_and_b32_e32 v16, 6, v0
	v_lshrrev_b32_e32 v3, 7, v2
	v_lshrrev_b32_e32 v4, 3, v2
	v_lshlrev_b32_e32 v5, 6, v2
	v_lshlrev_b32_e32 v6, 2, v2
	v_add_u32_e32 v3, v3, v16
	v_and_or_b32 v4, v4, 14, v17
	v_and_b32_e32 v5, 0x3c0, v5
	v_and_b32_e32 v6, 32, v6
	v_lshl_add_u32 v3, v3, 14, 0
	v_lshlrev_b32_e32 v4, 10, v4
	v_bitop3_b32 v5, v5, v6, v18 bitop3:0x36
	s_waitcnt lgkmcnt(0)
	s_barrier
	v_add3_u32 v3, v3, v5, v4
	s_addc_u32 s7, s9, s7
	v_and_b32_e32 v0, 0x1f0, v190
	ds_read_b128 v[4:7], v3
	v_ashrrev_i32_e32 v3, 31, v2
	v_lshl_add_u64 v[0:1], s[6:7], 0, v[0:1]
	v_lshlrev_b64 v[8:9], 12, v[2:3]
	v_add_u32_e32 v14, 2, v2
	v_lshl_add_u64 v[12:13], v[0:1], 0, v[8:9]
	v_lshrrev_b32_e32 v3, 7, v14
	v_lshrrev_b32_e32 v8, 3, v14
	v_lshlrev_b32_e32 v9, 6, v14
	v_lshlrev_b32_e32 v10, 2, v14
	v_add_u32_e32 v3, v3, v16
	v_and_or_b32 v8, v8, 14, v17
	v_and_b32_e32 v9, 0x3c0, v9
	v_and_b32_e32 v10, 32, v10
	v_lshl_add_u32 v3, v3, 14, 0
	v_lshlrev_b32_e32 v8, 10, v8
	v_bitop3_b32 v9, v9, v10, v18 bitop3:0x36
	v_add3_u32 v3, v3, v9, v8
	ds_read_b128 v[8:11], v3
	v_ashrrev_i32_e32 v15, 31, v14
	s_waitcnt lgkmcnt(1)
	global_store_dwordx4 v[12:13], v[4:7], off
	s_nop 1
	v_lshlrev_b64 v[4:5], 12, v[14:15]
	v_lshl_add_u64 v[4:5], v[0:1], 0, v[4:5]
	s_waitcnt lgkmcnt(0)
	global_store_dwordx4 v[4:5], v[8:11], off
	v_add_u32_e32 v14, 6, v2
	v_ashrrev_i32_e32 v15, 31, v14
	v_add_u32_e32 v8, 4, v2
	v_lshrrev_b32_e32 v3, 7, v8
	v_lshrrev_b32_e32 v4, 3, v8
	v_lshlrev_b32_e32 v5, 6, v8
	v_lshlrev_b32_e32 v6, 2, v8
	v_add_u32_e32 v3, v3, v16
	v_and_or_b32 v4, v4, 14, v17
	v_and_b32_e32 v5, 0x3c0, v5
	v_and_b32_e32 v6, 32, v6
	v_lshl_add_u32 v3, v3, 14, 0
	v_lshlrev_b32_e32 v4, 10, v4
	v_bitop3_b32 v5, v5, v6, v18 bitop3:0x36
	v_ashrrev_i32_e32 v9, 31, v8
	v_add3_u32 v3, v3, v5, v4
	v_lshlrev_b64 v[8:9], 12, v[8:9]
	ds_read_b128 v[4:7], v3
	v_lshl_add_u64 v[12:13], v[0:1], 0, v[8:9]
	v_lshrrev_b32_e32 v3, 7, v14
	v_lshrrev_b32_e32 v8, 3, v14
	v_lshlrev_b32_e32 v9, 6, v14
	v_lshlrev_b32_e32 v10, 2, v14
	v_add_u32_e32 v3, v3, v16
	v_and_or_b32 v8, v8, 14, v17
	v_and_b32_e32 v9, 0x3c0, v9
	v_and_b32_e32 v10, 32, v10
	v_lshl_add_u32 v3, v3, 14, 0
	v_lshlrev_b32_e32 v8, 10, v8
	v_bitop3_b32 v9, v9, v10, v18 bitop3:0x36
	v_add3_u32 v3, v3, v9, v8
	ds_read_b128 v[8:11], v3
	s_waitcnt lgkmcnt(1)
	global_store_dwordx4 v[12:13], v[4:7], off
	s_nop 1
	v_lshlrev_b64 v[4:5], 12, v[14:15]
	v_lshl_add_u64 v[4:5], v[0:1], 0, v[4:5]
	s_waitcnt lgkmcnt(0)
	global_store_dwordx4 v[4:5], v[8:11], off
	v_add_u32_e32 v14, 10, v2
	v_ashrrev_i32_e32 v15, 31, v14
	v_add_u32_e32 v8, 8, v2
	v_lshrrev_b32_e32 v3, 7, v8
	v_lshrrev_b32_e32 v4, 3, v8
	v_lshlrev_b32_e32 v5, 6, v8
	v_lshlrev_b32_e32 v6, 2, v8
	v_add_u32_e32 v3, v3, v16
	v_and_or_b32 v4, v4, 14, v17
	v_and_b32_e32 v5, 0x3c0, v5
	v_and_b32_e32 v6, 32, v6
	v_lshl_add_u32 v3, v3, 14, 0
	v_lshlrev_b32_e32 v4, 10, v4
	v_bitop3_b32 v5, v5, v6, v18 bitop3:0x36
	v_ashrrev_i32_e32 v9, 31, v8
	v_add3_u32 v3, v3, v5, v4
	v_lshlrev_b64 v[8:9], 12, v[8:9]
	ds_read_b128 v[4:7], v3
	v_lshl_add_u64 v[12:13], v[0:1], 0, v[8:9]
	v_lshrrev_b32_e32 v3, 7, v14
	v_lshrrev_b32_e32 v8, 3, v14
	v_lshlrev_b32_e32 v9, 6, v14
	v_lshlrev_b32_e32 v10, 2, v14
	v_add_u32_e32 v3, v3, v16
	v_and_or_b32 v8, v8, 14, v17
	v_and_b32_e32 v9, 0x3c0, v9
	v_and_b32_e32 v10, 32, v10
	v_lshl_add_u32 v3, v3, 14, 0
	v_lshlrev_b32_e32 v8, 10, v8
	v_bitop3_b32 v9, v9, v10, v18 bitop3:0x36
	v_add3_u32 v3, v3, v9, v8
	ds_read_b128 v[8:11], v3
	s_waitcnt lgkmcnt(1)
	global_store_dwordx4 v[12:13], v[4:7], off
	s_nop 1
	v_lshlrev_b64 v[4:5], 12, v[14:15]
	v_lshl_add_u64 v[4:5], v[0:1], 0, v[4:5]
	s_waitcnt lgkmcnt(0)
	global_store_dwordx4 v[4:5], v[8:11], off
	v_add_u32_e32 v14, 14, v2
	v_ashrrev_i32_e32 v15, 31, v14
	v_add_u32_e32 v8, 12, v2
	v_lshrrev_b32_e32 v3, 7, v8
	v_lshrrev_b32_e32 v4, 3, v8
	v_lshlrev_b32_e32 v5, 6, v8
	v_lshlrev_b32_e32 v6, 2, v8
	v_add_u32_e32 v3, v3, v16
	v_and_or_b32 v4, v4, 14, v17
	v_and_b32_e32 v5, 0x3c0, v5
	v_and_b32_e32 v6, 32, v6
	v_lshl_add_u32 v3, v3, 14, 0
	v_lshlrev_b32_e32 v4, 10, v4
	v_bitop3_b32 v5, v5, v6, v18 bitop3:0x36
	v_ashrrev_i32_e32 v9, 31, v8
	v_add3_u32 v3, v3, v5, v4
	v_lshlrev_b64 v[8:9], 12, v[8:9]
	ds_read_b128 v[4:7], v3
	v_lshl_add_u64 v[12:13], v[0:1], 0, v[8:9]
	v_lshrrev_b32_e32 v3, 7, v14
	v_lshrrev_b32_e32 v8, 3, v14
	v_lshlrev_b32_e32 v9, 6, v14
	v_lshlrev_b32_e32 v10, 2, v14
	v_add_u32_e32 v3, v3, v16
	v_and_or_b32 v8, v8, 14, v17
	v_and_b32_e32 v9, 0x3c0, v9
	v_and_b32_e32 v10, 32, v10
	v_lshl_add_u32 v3, v3, 14, 0
	v_lshlrev_b32_e32 v8, 10, v8
	v_bitop3_b32 v9, v9, v10, v18 bitop3:0x36
	v_add3_u32 v3, v3, v9, v8
	ds_read_b128 v[8:11], v3
	s_waitcnt lgkmcnt(1)
	global_store_dwordx4 v[12:13], v[4:7], off
	s_nop 1
	v_lshlrev_b64 v[4:5], 12, v[14:15]
	v_lshl_add_u64 v[4:5], v[0:1], 0, v[4:5]
	s_waitcnt lgkmcnt(0)
	global_store_dwordx4 v[4:5], v[8:11], off
	v_add_u32_e32 v14, 18, v2
	v_ashrrev_i32_e32 v15, 31, v14
	v_add_u32_e32 v8, 16, v2
	v_lshrrev_b32_e32 v3, 7, v8
	v_lshrrev_b32_e32 v4, 3, v8
	v_lshlrev_b32_e32 v5, 6, v8
	v_lshlrev_b32_e32 v6, 2, v8
	v_add_u32_e32 v3, v3, v16
	v_and_or_b32 v4, v4, 14, v17
	v_and_b32_e32 v5, 0x3c0, v5
	v_and_b32_e32 v6, 32, v6
	v_lshl_add_u32 v3, v3, 14, 0
	v_lshlrev_b32_e32 v4, 10, v4
	v_bitop3_b32 v5, v5, v6, v18 bitop3:0x36
	v_ashrrev_i32_e32 v9, 31, v8
	v_add3_u32 v3, v3, v5, v4
	v_lshlrev_b64 v[8:9], 12, v[8:9]
	ds_read_b128 v[4:7], v3
	v_lshl_add_u64 v[12:13], v[0:1], 0, v[8:9]
	v_lshrrev_b32_e32 v3, 7, v14
	v_lshrrev_b32_e32 v8, 3, v14
	v_lshlrev_b32_e32 v9, 6, v14
	v_lshlrev_b32_e32 v10, 2, v14
	v_add_u32_e32 v3, v3, v16
	v_and_or_b32 v8, v8, 14, v17
	v_and_b32_e32 v9, 0x3c0, v9
	v_and_b32_e32 v10, 32, v10
	v_lshl_add_u32 v3, v3, 14, 0
	v_lshlrev_b32_e32 v8, 10, v8
	v_bitop3_b32 v9, v9, v10, v18 bitop3:0x36
	v_add3_u32 v3, v3, v9, v8
	ds_read_b128 v[8:11], v3
	s_waitcnt lgkmcnt(1)
	global_store_dwordx4 v[12:13], v[4:7], off
	s_nop 1
	v_lshlrev_b64 v[4:5], 12, v[14:15]
	v_lshl_add_u64 v[4:5], v[0:1], 0, v[4:5]
	s_waitcnt lgkmcnt(0)
	global_store_dwordx4 v[4:5], v[8:11], off
	v_add_u32_e32 v14, 22, v2
	v_ashrrev_i32_e32 v15, 31, v14
	v_add_u32_e32 v8, 20, v2
	v_lshrrev_b32_e32 v3, 7, v8
	v_lshrrev_b32_e32 v4, 3, v8
	v_lshlrev_b32_e32 v5, 6, v8
	v_lshlrev_b32_e32 v6, 2, v8
	v_add_u32_e32 v3, v3, v16
	v_and_or_b32 v4, v4, 14, v17
	v_and_b32_e32 v5, 0x3c0, v5
	v_and_b32_e32 v6, 32, v6
	v_lshl_add_u32 v3, v3, 14, 0
	v_lshlrev_b32_e32 v4, 10, v4
	v_bitop3_b32 v5, v5, v6, v18 bitop3:0x36
	v_ashrrev_i32_e32 v9, 31, v8
	v_add3_u32 v3, v3, v5, v4
	v_lshlrev_b64 v[8:9], 12, v[8:9]
	ds_read_b128 v[4:7], v3
	v_lshl_add_u64 v[12:13], v[0:1], 0, v[8:9]
	v_lshrrev_b32_e32 v3, 7, v14
	v_lshrrev_b32_e32 v8, 3, v14
	v_lshlrev_b32_e32 v9, 6, v14
	v_lshlrev_b32_e32 v10, 2, v14
	v_add_u32_e32 v3, v3, v16
	v_and_or_b32 v8, v8, 14, v17
	v_and_b32_e32 v9, 0x3c0, v9
	v_and_b32_e32 v10, 32, v10
	v_lshl_add_u32 v3, v3, 14, 0
	v_lshlrev_b32_e32 v8, 10, v8
	v_bitop3_b32 v9, v9, v10, v18 bitop3:0x36
	v_add3_u32 v3, v3, v9, v8
	ds_read_b128 v[8:11], v3
	s_waitcnt lgkmcnt(1)
	global_store_dwordx4 v[12:13], v[4:7], off
	s_nop 1
	v_lshlrev_b64 v[4:5], 12, v[14:15]
	v_lshl_add_u64 v[4:5], v[0:1], 0, v[4:5]
	s_waitcnt lgkmcnt(0)
	global_store_dwordx4 v[4:5], v[8:11], off
	v_add_u32_e32 v14, 26, v2
	v_ashrrev_i32_e32 v15, 31, v14
	v_add_u32_e32 v8, 24, v2
	v_lshrrev_b32_e32 v3, 7, v8
	v_lshrrev_b32_e32 v4, 3, v8
	v_lshlrev_b32_e32 v5, 6, v8
	v_lshlrev_b32_e32 v6, 2, v8
	v_add_u32_e32 v3, v3, v16
	v_and_or_b32 v4, v4, 14, v17
	v_and_b32_e32 v5, 0x3c0, v5
	v_and_b32_e32 v6, 32, v6
	v_lshl_add_u32 v3, v3, 14, 0
	v_lshlrev_b32_e32 v4, 10, v4
	v_bitop3_b32 v5, v5, v6, v18 bitop3:0x36
	v_ashrrev_i32_e32 v9, 31, v8
	v_add3_u32 v3, v3, v5, v4
	v_lshlrev_b64 v[8:9], 12, v[8:9]
	ds_read_b128 v[4:7], v3
	v_lshl_add_u64 v[12:13], v[0:1], 0, v[8:9]
	v_lshrrev_b32_e32 v3, 7, v14
	v_lshrrev_b32_e32 v8, 3, v14
	v_lshlrev_b32_e32 v9, 6, v14
	v_lshlrev_b32_e32 v10, 2, v14
	v_add_u32_e32 v3, v3, v16
	v_and_or_b32 v8, v8, 14, v17
	v_and_b32_e32 v9, 0x3c0, v9
	v_and_b32_e32 v10, 32, v10
	v_lshl_add_u32 v3, v3, 14, 0
	v_lshlrev_b32_e32 v8, 10, v8
	v_bitop3_b32 v9, v9, v10, v18 bitop3:0x36
	v_add3_u32 v3, v3, v9, v8
	ds_read_b128 v[8:11], v3
	s_waitcnt lgkmcnt(1)
	global_store_dwordx4 v[12:13], v[4:7], off
	s_nop 1
	v_lshlrev_b64 v[4:5], 12, v[14:15]
	v_lshl_add_u64 v[4:5], v[0:1], 0, v[4:5]
	s_waitcnt lgkmcnt(0)
	global_store_dwordx4 v[4:5], v[8:11], off
	s_nop 1
	v_add_u32_e32 v8, 28, v2
	v_lshrrev_b32_e32 v3, 7, v8
	v_lshrrev_b32_e32 v4, 3, v8
	v_lshlrev_b32_e32 v5, 6, v8
	v_lshlrev_b32_e32 v6, 2, v8
	v_add_u32_e32 v3, v3, v16
	v_and_or_b32 v4, v4, 14, v17
	v_and_b32_e32 v5, 0x3c0, v5
	v_and_b32_e32 v6, 32, v6
	v_lshl_add_u32 v3, v3, 14, 0
	v_lshlrev_b32_e32 v4, 10, v4
	v_bitop3_b32 v5, v5, v6, v18 bitop3:0x36
	v_ashrrev_i32_e32 v9, 31, v8
	v_add3_u32 v3, v3, v5, v4
	v_lshlrev_b64 v[8:9], 12, v[8:9]
	v_add_u32_e32 v2, 30, v2
	ds_read_b128 v[4:7], v3
	v_lshl_add_u64 v[12:13], v[0:1], 0, v[8:9]
	v_lshrrev_b32_e32 v3, 7, v2
	v_lshrrev_b32_e32 v8, 3, v2
	v_lshlrev_b32_e32 v9, 6, v2
	v_lshlrev_b32_e32 v10, 2, v2
	v_add_u32_e32 v3, v3, v16
	v_and_or_b32 v8, v8, 14, v17
	v_and_b32_e32 v9, 0x3c0, v9
	v_and_b32_e32 v10, 32, v10
	v_lshl_add_u32 v3, v3, 14, 0
	v_lshlrev_b32_e32 v8, 10, v8
	v_bitop3_b32 v9, v9, v10, v18 bitop3:0x36
	v_add3_u32 v3, v3, v9, v8
	ds_read_b128 v[8:11], v3
	v_ashrrev_i32_e32 v3, 31, v2
	v_lshlrev_b64 v[2:3], 12, v[2:3]
	v_lshl_add_u64 v[0:1], v[0:1], 0, v[2:3]
	s_waitcnt lgkmcnt(1)
	global_store_dwordx4 v[12:13], v[4:7], off
	s_waitcnt lgkmcnt(0)
	global_store_dwordx4 v[0:1], v[8:11], off
	s_waitcnt lgkmcnt(0)
	s_barrier
.LBB0_980:
	s_branch .LBB0_1004
.Lsq_B:
	s_and_b64 vcc, exec, s[68:69]
	s_waitcnt vmcnt(13)
	v_mbcnt_lo_u32_b32 v8, -1, 0
	v_mbcnt_hi_u32_b32 v8, -1, v8
	s_cbranch_vccnz .Lsq_wait
	s_ashr_i32 s60, s2, 31
	s_lshr_b32 s6, s60, 29
	s_add_i32 s9, s2, s6
	s_and_b32 s6, s9, -8
	s_sub_i32 s14, s2, s6
	s_mov_b64 s[4:5], s[54:55]
	s_mov_b64 s[54:55], s[42:43]
	s_cmp_gt_i32 s14, -1
	s_cbranch_scc0 .LBB0_983
	s_lshl_b32 s8, s14, 5
	s_mov_b32 s42, s90
	s_cbranch_execz .LBB0_984
	s_branch .LBB0_985

.LBB0_1003:
	s_waitcnt vmcnt(0)
	v_readlane_b32 s68, v250, 9
	s_mov_b32 s90, s42
	s_mov_b64 s[42:43], s[54:55]
	s_mov_b64 s[54:55], s[4:5]
	v_readlane_b32 s69, v250, 10
	s_barrier
	s_branch .Lsq_wait
.LBB0_1004:
	s_mov_b32 s100, 0
	s_and_b64 vcc, exec, s[42:43]
	s_mov_b64 s[8:9], 0
	s_cbranch_vccnz .LBB0_1006
	v_mbcnt_lo_u32_b32 v0, -1, 0
	v_mbcnt_hi_u32_b32 v0, -1, v0
	s_nop 0
	v_cmp_eq_u32_e32 vcc, 0, v0
	s_and_b64 s[8:9], vcc, exec
.LBB0_1006:
	s_waitcnt vmcnt(0)
	s_waitcnt vmcnt(0)
	s_barrier
	s_and_saveexec_b64 s[6:7], s[8:9]
	s_cbranch_execz .LBB0_1058
	s_add_i32 s8, 0, 0x23fc0
	v_mov_b32_e32 v0, s8
	s_waitcnt vmcnt(0) expcnt(0) lgkmcnt(0)
	ds_read_b32 v2, v0
	s_add_i32 s8, 0, 0x23fc4
	v_mov_b32_e32 v0, s8
	ds_read_b32 v0, v0
	s_waitcnt lgkmcnt(1)
	v_cmp_ne_u32_e32 vcc, 0, v2
	s_cbranch_vccnz .LBB0_1022
	s_load_dword s8, s[0:1], 0xc8
	s_mov_b32 s61, 1
	v_mov_b32_e32 v16, 0
	s_waitcnt lgkmcnt(0)
	s_mul_i32 s60, s47, s8
	s_add_u32 s8, s50, 0x80200
	s_addc_u32 s9, s51, 0
	s_add_u32 s14, s50, 0x80400
	s_addc_u32 s15, s51, 0
	s_add_u32 s16, s50, 0x80500
	s_addc_u32 s17, s51, 0
	s_add_u32 s18, s50, 0x80600
	s_addc_u32 s19, s51, 0
	s_add_u32 s20, s50, 0x80700
	s_addc_u32 s21, s51, 0
	s_add_u32 s22, s50, 0x80800
	s_addc_u32 s23, s51, 0
	s_add_u32 s24, s50, 0x80900
	s_addc_u32 s25, s51, 0
	s_add_u32 s26, s50, 0x80a00
	s_addc_u32 s27, s51, 0
	s_add_u32 s28, s50, 0x80b00
	s_addc_u32 s29, s51, 0
	s_add_u32 s30, s50, 0x80c00
	s_addc_u32 s31, s51, 0
	s_add_u32 s34, s50, 0x80d00
	s_addc_u32 s35, s51, 0
	s_add_u32 s36, s50, 0x80e00
	s_addc_u32 s37, s51, 0
	s_add_u32 s38, s50, 0x80f00
	s_addc_u32 s39, s51, 0
	s_add_u32 s40, s50, 0x81000
	s_addc_u32 s41, s51, 0
	s_add_u32 s44, s50, 0x81100
	s_addc_u32 s45, s51, 0
	s_add_u32 s64, s50, 0x81200
	s_addc_u32 s65, s51, 0
	s_add_u32 s66, s50, 0x81300
	s_mul_i32 s60, s60, s46
	s_addc_u32 s67, s51, 0
	s_branch .LBB0_1010

.LBB0_1024:
	s_or_b64 exec, exec, s[16:17]
	buffer_inv sc1
	v_cvt_f32_u32_e32 v4, v2
	s_waitcnt vmcnt(1)
	v_readfirstlane_b32 s14, v3
	v_sub_u32_e32 v3, 0, v2
	v_rcp_iflag_f32_e32 v4, v4
	v_add_u32_e32 v5, s14, v1
	v_mul_f32_e32 v4, 0x4f7ffffe, v4
	v_cvt_u32_f32_e32 v4, v4
	v_mul_lo_u32 v1, v3, v4
	v_mul_hi_u32 v1, v4, v1
	v_add_u32_e32 v1, v4, v1
	v_mul_hi_u32 v1, v5, v1
	v_mul_lo_u32 v3, v1, v2
	v_sub_u32_e32 v3, v5, v3
	v_add_u32_e32 v4, 1, v1
	v_cmp_ge_u32_e32 vcc, v3, v2
	s_nop 1
	v_cndmask_b32_e32 v1, v1, v4, vcc
	v_sub_u32_e32 v4, v3, v2
	v_cndmask_b32_e32 v3, v3, v4, vcc
	v_add_u32_e32 v4, 1, v1
	v_cmp_ge_u32_e32 vcc, v3, v2
	v_add_u32_e32 v3, 1, v5
	s_nop 0
	v_cndmask_b32_e32 v1, v1, v4, vcc
	v_mul_lo_u32 v4, v2, v1
	v_add_u32_e32 v2, v4, v2
	v_cmp_ne_u32_e32 vcc, v3, v2
	s_and_saveexec_b64 s[14:15], vcc
	s_xor_b64 s[14:15], exec, s[14:15]
	s_cbranch_execz .LBB0_1038
	v_readfirstlane_b32 s99, v1
	s_mov_b32 s100, 1

.Lxg_skip_5:
	s_cbranch_vccz .Lsq_glast
	v_readfirstlane_b32 s99, v2
	s_mov_b32 s100, 2
	s_mov_b64 s[14:15], exec
	s_branch .LBB0_1055
.Lsq_glast:
	v_mov_b32_e32 v2, 1
	global_atomic_add v[0:1], v2, off
	s_mov_b32 s100, 0
	s_mov_b64 s[14:15], exec

.LBB0_1058:
	s_or_b64 exec, exec, s[6:7]
	s_waitcnt lgkmcnt(0)
	s_branch .Lsq_B

.Lsq_done:
	v_readlane_b32 s4, v250, 3
	v_readlane_b32 s5, v250, 4
	v_mov_b32_e32 v184, 0x7f7f7f7f
	s_andn2_b64 vcc, exec, s[4:5]
	s_waitcnt lgkmcnt(0)
	s_barrier
	v_mbcnt_lo_u32_b32 v9, -1, 0
	v_mbcnt_hi_u32_b32 v9, -1, v9
	s_cbranch_vccnz .LBB0_1074
	v_lshl_add_u32 v0, v9, 4, s3
	v_add_u32_e32 v1, 0x2000, v0
	v_ashrrev_i32_e32 v2, 31, v1
	v_lshrrev_b32_e32 v2, 22, v2
	v_add_u32_e32 v2, v1, v2
	v_ashrrev_i32_e32 v8, 10, v2
	v_mul_i32_i24_e32 v2, 0x400, v8
	v_sub_u32_e32 v1, v1, v2
	v_lshrrev_b32_e32 v2, 4, v1
	v_bitop3_b32 v1, v2, v1, 32 bitop3:0x6c
	v_ashrrev_i32_e32 v2, 31, v1
	v_lshrrev_b32_e32 v2, 26, v2
	v_add_u32_e32 v2, v1, v2
	v_ashrrev_i32_e32 v10, 6, v2
	v_lshlrev_b32_e32 v3, 3, v8
	v_and_b32_e32 v2, 0xffc0, v2
	v_and_b32_e32 v3, -16, v3
	v_sub_u32_e32 v1, v1, v2
	v_add_u32_e32 v3, v10, v3
	v_lshrrev_b16_e32 v2, 7, v1
	v_and_b32_e32 v4, 3, v10
	s_mov_b32 s6, 0x1fffe0
	v_lshrrev_b32_e32 v5, 2, v3
	v_lshlrev_b32_e32 v6, 1, v3
	v_and_b32_e32 v2, 1, v2
	v_and_or_b32 v4, v3, s6, v4
	v_and_b32_e32 v5, 4, v5
	v_and_b32_e32 v6, 24, v6
	v_add_u16_e32 v1, v1, v2
	v_mov_b32_e32 v2, 1
	v_or3_b32 v4, v4, v5, v6
	v_lshlrev_b32_e32 v5, 5, v8
	v_ashrrev_i16_sdwa v1, v2, sext(v1) dst_sel:DWORD dst_unused:UNUSED_PAD src0_sel:DWORD src1_sel:BYTE_0
	v_and_b32_e32 v5, 32, v5
	v_bfe_i32 v11, v1, 0, 16
	v_add_lshl_u32 v1, v5, v11, 1
	v_lshl_add_u32 v160, v4, 11, v1
	v_lshl_add_u32 v162, v3, 11, v1
	v_ashrrev_i32_e32 v1, 31, v0
	v_lshrrev_b32_e32 v1, 22, v1
	v_add_u32_e32 v1, v0, v1
	v_ashrrev_i32_e32 v12, 10, v1
	v_mul_i32_i24_e32 v1, 0x400, v12
	v_sub_u32_e32 v0, v0, v1
	v_lshrrev_b32_e32 v1, 4, v0
	v_bitop3_b32 v0, v1, v0, 32 bitop3:0x6c
	v_ashrrev_i32_e32 v1, 31, v0
	v_lshrrev_b32_e32 v1, 26, v1
	v_add_u32_e32 v1, v0, v1
	v_lshlrev_b32_e32 v3, 3, v12
	s_add_u32 s36, s50, 0x6300000
	v_ashrrev_i32_e32 v13, 6, v1
	v_and_b32_e32 v3, -16, v3
	s_addc_u32 s37, s51, 0
	v_add_u32_e32 v3, v13, v3
	v_and_b32_e32 v4, 3, v13
	s_ashr_i32 s38, s2, 31
	v_and_or_b32 v4, v3, s6, v4
	s_lshr_b32 s6, s38, 29
	s_add_i32 s6, s2, s6
	s_ashr_i32 s7, s6, 3
	s_and_b32 s6, s6, -8
	s_sub_i32 s6, s2, s6
	s_cmp_lt_i32 s6, 0
	s_movk_i32 s39, 0xb1
	s_cselect_b32 s8, s39, 0xb0
	s_mul_i32 s6, s6, s8
	s_add_i32 s6, s6, s7
	s_mul_hi_i32 s7, s6, 0x2e8ba2e9
	s_lshr_b32 s8, s7, 31
	s_ashr_i32 s7, s7, 6
	s_add_i32 s7, s7, s8
	s_lshl_b32 s8, s7, 3
	s_mulk_i32 s7, 0x160
	s_sub_i32 s7, s6, s7
	s_sext_i32_i16 s6, s7
	s_bfe_u32 s6, s6, 0x3001c
	s_add_i32 s9, s7, s6
	s_sext_i32_i16 s6, s9
	s_and_b32 s9, s9, 0xfff8
	s_sub_i32 s7, s7, s9
	s_sext_i32_i16 s7, s7
	v_lshrrev_b32_e32 v5, 2, v3
	v_lshlrev_b32_e32 v6, 1, v3
	v_and_b32_e32 v1, 0xc0, v1
	s_lshr_b32 s6, s6, 3
	s_add_i32 s8, s8, s7
	v_and_b32_e32 v5, 4, v5
	v_and_b32_e32 v6, 24, v6
	v_sub_u32_e32 v0, v0, v1
	s_ashr_i32 s9, s8, 31
	s_bfe_i64 s[16:17], s[6:7], 0x100000
	v_or3_b32 v4, v4, v5, v6
	v_lshlrev_b32_e32 v5, 5, v12
	v_ashrrev_i16_sdwa v0, v2, sext(v0) dst_sel:DWORD dst_unused:UNUSED_PAD src0_sel:DWORD src1_sel:BYTE_0
	s_lshl_b64 s[14:15], s[8:9], 19
	s_lshl_b64 s[16:17], s[16:17], 19
	v_and_b32_e32 v5, 32, v5
	v_bfe_i32 v14, v0, 0, 16
	s_add_u32 s30, s36, s16
	v_add_lshl_u32 v0, v5, v14, 1
	s_addc_u32 s31, s37, s17
	s_add_i32 s40, s3, 0
	v_lshl_add_u32 v164, v4, 11, v0
	s_add_i32 m0, s40, 0x10000
	v_lshl_add_u32 v166, v3, 11, v0
	global_load_lds_dwordx4 v164, s[30:31]
	s_add_i32 m0, s40, 0x12000
	s_add_u32 s16, s30, 0x40000
	global_load_lds_dwordx4 v160, s[30:31]
	s_addc_u32 s17, s31, 0
	s_add_i32 m0, s40, 0x14000
	v_mov_b32_e32 v165, 0
	global_load_lds_dwordx4 v164, s[16:17]
	s_add_i32 m0, s40, 0x16000
	s_add_u32 s28, s12, s14
	s_addc_u32 s29, s13, s15
	s_add_i32 s41, s40, 0x2000
	global_load_lds_dwordx4 v160, s[16:17]
	s_mov_b32 m0, s40
	s_add_u32 s14, s28, 0x40000
	global_load_lds_dwordx4 v166, s[28:29]
	s_mov_b32 m0, s41
	s_addc_u32 s15, s29, 0
	s_add_i32 s44, s40, 0x4000
	global_load_lds_dwordx4 v162, s[28:29]
	s_mov_b32 m0, s44
	s_add_i32 s45, s40, 0x6000
	global_load_lds_dwordx4 v166, s[14:15]
	s_mov_b32 m0, s45
	v_mov_b32_e32 v161, v165
	global_load_lds_dwordx4 v162, s[14:15]
	v_mov_b32_e32 v167, v165
	v_mov_b32_e32 v163, v165
	s_cmp_eq_u32 s88, 1
	s_mov_b32 s60, 0
	v_lshl_add_u64 v[6:7], s[30:31], 0, v[164:165]
	v_lshl_add_u64 v[4:5], s[30:31], 0, v[160:161]
	v_lshl_add_u64 v[0:1], s[28:29], 0, v[166:167]
	s_cselect_b64 s[14:15], -1, 0
	s_cmp_lg_u32 s88, 1
	v_lshl_add_u64 v[2:3], s[28:29], 0, v[162:163]
	s_cbranch_scc1 .LBB0_1061
	s_barrier
